# stagger phase order across workgroup groups: groups with bid bit 6 run attention before gMLP (independent phases), so the bandwidth-bound gMLP overlaps the issue-bound attention
# speedup vs baseline: 1.0032x; 1.0032x over previous
; __global__ void __launch_bounds__(NWAVES * 64, 2) fwd_kernel(Args args_) {
;     ...
;         const int l = pe == 0 ? 0 : (pe - 1) / PH_PER_LAYER, s = pe == 0 ? -1 : (pe - 1) % PH_PER_LAYER;
;         switch ((NPASS > 1 && ph < N_PHASES && ((PROBE_SKIP >> (s + 1)) & 1)) ? 99 : s) {
.LBB0_10:
	s_add_i32 s0, s64, -1
	s_mul_hi_i32 s1, s0, 0x92492493
	s_add_i32 s1, s1, s0
	s_lshr_b32 s5, s1, 31
	s_ashr_i32 s1, s1, 2
	s_add_i32 s74, s1, s5
	s_mul_i32 s1, s74, 7
	s_sub_i32 s5, s0, s1
	s_add_i32 s0, s5, -1
	s_cmp_lt_u32 s0, 2
	s_cselect_b32 s0, 3, 0
	s_bitcmp1_b32 s2, 6
	s_cselect_b32 s0, s0, 0
	s_xor_b32 s5, s5, s0
	s_cmp_lt_i32 s5, 3
	s_mov_b64 s[0:1], -1
	s_cbranch_scc1 .LBB0_211
	s_cmp_lt_i32 s5, 5
	s_cbranch_scc1 .LBB0_161
	s_cmp_lt_i32 s5, 6
	s_cbranch_scc1 .LBB0_139
	s_cmp_eq_u32 s5, 6
	s_cbranch_scc0 .LBB0_138
	s_add_i32 s0, s64, -8
	s_cmp_gt_u32 s0, -14
	s_cselect_b64 s[0:1], -1, 0
	s_mov_b64 s[6:7], s[92:93]
	v_mov_b32_e32 v1, v218
	s_waitcnt lgkmcnt(0)
	s_mov_b64 s[14:15], 0
	s_and_b64 vcc, exec, s[0:1]
	s_cbranch_vccnz .LBB0_16
	s_load_dwordx2 s[14:15], s[6:7], 0x80

; #define LAS __attribute__((address_space(3)))
; __device__ __forceinline__ unsigned xb_xcc_id() { return (unsigned)__builtin_amdgcn_s_getreg((3 << 11) | 20) & 0xFu; }
; #define KARGS(A) KArgs A = (KArgs)__builtin_amdgcn_kernarg_segment_ptr(); asm volatile("" : "+s"(A))
; __global__ void __launch_bounds__(NWAVES * 64, 2) fwd_kernel(Args args_) {
;     ...
;         if (ph + 1 < ph_hi && s != 1) {
;             if (ph_hi < 0) cg::this_grid().sync();
;             { KARGS(Ab); XcdBarrier b; b.bar = (unsigned*)(Ab->ws + WS_CTL) + CW_BAR; b.x = xb_xcc_id(); b.st = (volatile LAS unsigned*)((LAS unsigned char*)lds + MISC_OFF) + 8; xcd_barrier(b); }
;         }
.LBB0_571:
	s_add_i32 s0, s5, -1
	s_cmp_lt_u32 s0, 2
	s_cselect_b32 s0, 3, 0
	s_bitcmp1_b32 s2, 6
	s_cselect_b32 s0, s0, 0
	s_xor_b32 s5, s5, s0
	s_add_i32 s64, s64, 1
	s_cmp_ge_i32 s64, s65
	s_cselect_b64 s[0:1], -1, 0
	s_cmp_eq_u32 s5, 1
	s_cselect_b64 s[6:7], -1, 0
	s_or_b64 s[6:7], s[0:1], s[6:7]
	s_and_b64 vcc, exec, s[6:7]
	s_cbranch_vccnz .LBB0_9
	s_andn2_b64 vcc, exec, s[96:97]
	s_cbranch_vccnz .LBB0_584
	s_waitcnt vmcnt(0) lgkmcnt(0)
	s_barrier
	s_mov_b64 s[6:7], exec
	v_readlane_b32 s8, v255, 38
	v_readlane_b32 s9, v255, 39
	s_and_b64 s[8:9], s[6:7], s[8:9]
	s_mov_b64 exec, s[8:9]
	s_cbranch_execz .LBB0_583
	v_readlane_b32 s8, v255, 2
	v_readlane_b32 s9, v255, 3
	buffer_wbl2 sc1
	s_load_dwordx2 s[8:9], s[8:9], 0x58
	s_mov_b64 s[10:11], exec
	v_mbcnt_lo_u32_b32 v2, s10, 0
	v_mbcnt_hi_u32_b32 v2, s11, v2
	v_cmp_eq_u32_e32 vcc, 0, v2
	s_waitcnt lgkmcnt(0)
	global_load_dword v1, v197, s[8:9] offset:40
	s_and_saveexec_b64 s[12:13], vcc
	s_cbranch_execz .LBB0_576
	s_bcnt1_i32_b64 s5, s[10:11]
	v_mov_b32_e32 v3, s5
	global_atomic_add v3, v197, v3, s[8:9] offset:32 sc0
